# hand-written phase_ffn_fixup: dwordx4 loads with wave-uniform row addressing instead of per-element dword loads
# speedup vs baseline: 1.0320x; 1.0320x over previous
.LBB0_2241:
	s_or_b64 exec, exec, s[2:3]
	s_mov_b64 s[10:11], s[0:1]
	s_mov_b64 s[12:13], s[0:1]
	s_mov_b64 s[14:15], s[0:1]
	s_mov_b64 s[16:17], s[0:1]
	s_mov_b64 s[8:9], s[0:1]
	v_mov_b32_e32 v0, v219
	v_readlane_b32 s2, v253, 49
	s_barrier
	s_mov_b64 s[2:3], exec
	v_readlane_b32 s4, v253, 49
	v_readlane_b32 s5, v254, 27
	s_load_dwordx2 s[6:7], s[0:1], 0xb0
	s_load_dwordx2 s[8:9], s[0:1], 0x88
	s_load_dwordx2 s[10:11], s[0:1], 0x90
	s_load_dwordx2 s[12:13], s[0:1], 0x30
	v_lshlrev_b32_e32 v12, 5, v219
	v_lshlrev_b32_e32 v14, 4, v219
	v_add_u32_e32 v13, 0x4000, v12
	s_lshr_b32 s4, s4, 9
	s_lshr_b32 s5, s5, 12
	s_lshl_b32 s24, s90, 15
	s_lshl_b32 s25, s90, 20
	s_waitcnt lgkmcnt(0)
	s_add_u32 s8, s8, s41
	s_addc_u32 s9, s9, 0
	s_add_u32 s10, s10, s24
	s_addc_u32 s11, s11, 0
	s_add_u32 s12, s12, s25
	s_addc_u32 s13, s13, 0
	s_add_u32 s26, s6, 0x34600000
	s_addc_u32 s27, s7, 0
	s_add_u32 s6, s6, 0x2e300000
	s_addc_u32 s7, s7, 0
	s_add_u32 s36, s8, 0x8000
	s_addc_u32 s37, s9, 0
	s_add_u32 s38, s8, 0x10000
	s_addc_u32 s39, s9, 0
	global_load_dwordx4 v[148:151], v12, s[8:9]
	global_load_dwordx4 v[152:155], v12, s[8:9] offset:16
	global_load_dwordx4 v[156:159], v13, s[8:9]
	global_load_dwordx4 v[160:163], v13, s[8:9] offset:16
	global_load_dwordx4 v[164:167], v12, s[36:37]
	global_load_dwordx4 v[168:171], v12, s[36:37] offset:16
	global_load_dwordx4 v[172:175], v13, s[36:37]
	global_load_dwordx4 v[176:179], v13, s[36:37] offset:16
	global_load_dwordx4 v[180:183], v12, s[38:39]
	global_load_dwordx4 v[184:187], v12, s[38:39] offset:16
	global_load_dwordx4 v[188:191], v13, s[38:39]
	global_load_dwordx4 v[192:195], v13, s[38:39] offset:16
	global_load_dwordx4 v[196:199], v12, s[10:11]
	global_load_dwordx4 v[200:203], v12, s[10:11] offset:16
	global_load_dwordx4 v[204:207], v13, s[10:11]
	global_load_dwordx4 v[208:211], v13, s[10:11] offset:16
.Lffx_loop:
	s_lshr_b32 s31, s4, 1
	s_and_b32 s32, s4, 1
	s_cmp_lt_u32 s4, 0x100
	s_cbranch_scc0 .Lffx_hi
	s_lshl_b32 s29, s31, 6
	s_add_u32 s29, s29, s32
	s_branch .Lffx_row
.Lffx_hi:
	s_sub_u32 s31, s31, 0x80
	s_lshl_b32 s29, s31, 4
	s_add_u32 s29, s29, s32
	s_add_u32 s29, s29, 0x2000
.Lffx_row:
	s_lshr_b32 s60, s29, 6
	s_lshl_b32 s60, s60, 2
	s_sub_u32 s61, s29, 0x2000
	s_lshr_b32 s61, s61, 4
	s_lshl_b32 s61, s61, 2
	s_add_u32 s61, s61, 0x200
	s_cmp_lt_u32 s29, 0x2000
	s_cselect_b32 s60, s60, s61
	s_add_u32 s61, s29, 2
	s_and_b32 s61, s61, 3
	s_add_u32 s60, s60, s61
	s_lshl_b32 s60, s60, 15
	s_add_u32 s42, s26, s60
	s_addc_u32 s43, s27, 0
	global_load_dwordx4 v[100:103], v12, s[42:43]
	global_load_dwordx4 v[104:107], v12, s[42:43] offset:16
	global_load_dwordx4 v[108:111], v13, s[42:43]
	global_load_dwordx4 v[112:115], v13, s[42:43] offset:16
	s_lshl_b32 s60, s29, 13
	s_add_u32 s48, s6, s60
	s_addc_u32 s49, s7, 0
	s_sub_u32 s62, s29, 1
	s_lshr_b32 s60, s62, 6
	s_lshl_b32 s60, s60, 2
	s_sub_u32 s61, s62, 0x2000
	s_lshr_b32 s61, s61, 4
	s_lshl_b32 s61, s61, 2
	s_add_u32 s61, s61, 0x200
	s_cmp_lt_u32 s62, 0x2000
	s_cselect_b32 s60, s60, s61
	s_add_u32 s61, s62, 2
	s_and_b32 s61, s61, 3
	s_add_u32 s60, s60, s61
	s_lshl_b32 s60, s60, 15
	s_add_u32 s44, s26, s60
	s_addc_u32 s45, s27, 0
	s_sub_u32 s62, s29, 2
	s_lshr_b32 s60, s62, 6
	s_lshl_b32 s60, s60, 2
	s_sub_u32 s61, s62, 0x2000
	s_lshr_b32 s61, s61, 4
	s_lshl_b32 s61, s61, 2
	s_add_u32 s61, s61, 0x200
	s_cmp_lt_u32 s62, 0x2000
	s_cselect_b32 s60, s60, s61
	s_add_u32 s61, s62, 2
	s_and_b32 s61, s61, 3
	s_add_u32 s60, s60, s61
	s_lshl_b32 s60, s60, 15
	s_add_u32 s46, s26, s60
	s_addc_u32 s47, s27, 0
	s_mov_b32 s50, 0
	s_mov_b32 s51, 0
	s_cmp_lt_u32 s29, 0x2010
	s_cbranch_scc0 .Lffx_samp
	s_cmp_lt_u32 s29, 1
	s_cselect_b32 s50, 1, 0
	s_cmp_lt_u32 s29, 2
	s_cselect_b32 s51, 1, 0
	s_branch .Lffx_ptrs
.Lffx_samp:
	s_sub_u32 s62, s29, 0x2010
	s_and_b32 s63, s62, 15
	s_lshr_b32 s62, s62, 4
	s_lshl_b32 s62, s62, 16
	s_add_u32 s64, s12, s62
	s_addc_u32 s65, s13, 0
	s_add_u32 s66, s64, 0x8000
	s_addc_u32 s67, s65, 0
	s_cmp_eq_u32 s63, 0
	s_cbranch_scc0 .Lffx_t1
	s_mov_b64 s[44:45], s[66:67]
	s_mov_b64 s[46:47], s[64:65]
	s_branch .Lffx_ptrs
.Lffx_t1:
	s_mov_b64 s[46:47], s[66:67]
.Lffx_ptrs:
	s_cmp_eq_u32 s50, 0
	s_cbranch_scc0 .Lffx_u1z
	global_load_dwordx4 v[116:119], v12, s[44:45]
	global_load_dwordx4 v[120:123], v12, s[44:45] offset:16
	global_load_dwordx4 v[124:127], v13, s[44:45]
	global_load_dwordx4 v[128:131], v13, s[44:45] offset:16
	s_branch .Lffx_u1d
.Lffx_u1z:
	v_mov_b32_e32 v116, 0
	v_mov_b32_e32 v117, 0
	v_mov_b32_e32 v118, 0
	v_mov_b32_e32 v119, 0
	v_mov_b32_e32 v120, 0
	v_mov_b32_e32 v121, 0
	v_mov_b32_e32 v122, 0
	v_mov_b32_e32 v123, 0
	v_mov_b32_e32 v124, 0
	v_mov_b32_e32 v125, 0
	v_mov_b32_e32 v126, 0
	v_mov_b32_e32 v127, 0
	v_mov_b32_e32 v128, 0
	v_mov_b32_e32 v129, 0
	v_mov_b32_e32 v130, 0
	v_mov_b32_e32 v131, 0
.Lffx_u1d:
	s_cmp_eq_u32 s51, 0
	s_cbranch_scc0 .Lffx_u2z
	global_load_dwordx4 v[132:135], v12, s[46:47]
	global_load_dwordx4 v[136:139], v12, s[46:47] offset:16
	global_load_dwordx4 v[140:143], v13, s[46:47]
	global_load_dwordx4 v[144:147], v13, s[46:47] offset:16
	s_branch .Lffx_u2d
.Lffx_u2z:
	v_mov_b32_e32 v132, 0
	v_mov_b32_e32 v133, 0
	v_mov_b32_e32 v134, 0
	v_mov_b32_e32 v135, 0
	v_mov_b32_e32 v136, 0
	v_mov_b32_e32 v137, 0
	v_mov_b32_e32 v138, 0
	v_mov_b32_e32 v139, 0
	v_mov_b32_e32 v140, 0
	v_mov_b32_e32 v141, 0
	v_mov_b32_e32 v142, 0
	v_mov_b32_e32 v143, 0
	v_mov_b32_e32 v144, 0
	v_mov_b32_e32 v145, 0
	v_mov_b32_e32 v146, 0
	v_mov_b32_e32 v147, 0
.Lffx_u2d:
	s_waitcnt vmcnt(0)
	v_mul_f32_e32 v16, v148, v132
	v_mul_f32_e32 v24, v156, v140
	v_mul_f32_e32 v17, v149, v133
	v_mul_f32_e32 v25, v157, v141
	v_mul_f32_e32 v18, v150, v134
	v_mul_f32_e32 v26, v158, v142
	v_mul_f32_e32 v19, v151, v135
	v_mul_f32_e32 v27, v159, v143
	v_mul_f32_e32 v20, v152, v136
	v_mul_f32_e32 v28, v160, v144
	v_mul_f32_e32 v21, v153, v137
	v_mul_f32_e32 v29, v161, v145
	v_mul_f32_e32 v22, v154, v138
	v_mul_f32_e32 v30, v162, v146
	v_mul_f32_e32 v23, v155, v139
	v_mul_f32_e32 v31, v163, v147
	v_fmac_f32_e32 v16, v164, v116
	v_fmac_f32_e32 v24, v172, v124
	v_fmac_f32_e32 v17, v165, v117
	v_fmac_f32_e32 v25, v173, v125
	v_fmac_f32_e32 v18, v166, v118
	v_fmac_f32_e32 v26, v174, v126
	v_fmac_f32_e32 v19, v167, v119
	v_fmac_f32_e32 v27, v175, v127
	v_fmac_f32_e32 v20, v168, v120
	v_fmac_f32_e32 v28, v176, v128
	v_fmac_f32_e32 v21, v169, v121
	v_fmac_f32_e32 v29, v177, v129
	v_fmac_f32_e32 v22, v170, v122
	v_fmac_f32_e32 v30, v178, v130
	v_fmac_f32_e32 v23, v171, v123
	v_fmac_f32_e32 v31, v179, v131
	v_fmac_f32_e32 v16, v180, v100
	v_fmac_f32_e32 v24, v188, v108
	v_fmac_f32_e32 v17, v181, v101
	v_fmac_f32_e32 v25, v189, v109
	v_fmac_f32_e32 v18, v182, v102
	v_fmac_f32_e32 v26, v190, v110
	v_fmac_f32_e32 v19, v183, v103
	v_fmac_f32_e32 v27, v191, v111
	v_fmac_f32_e32 v20, v184, v104
	v_fmac_f32_e32 v28, v192, v112
	v_fmac_f32_e32 v21, v185, v105
	v_fmac_f32_e32 v29, v193, v113
	v_fmac_f32_e32 v22, v186, v106
	v_fmac_f32_e32 v30, v194, v114
	v_fmac_f32_e32 v23, v187, v107
	v_fmac_f32_e32 v31, v195, v115
	v_add_f32_e32 v16, v196, v16
	v_add_f32_e32 v24, v204, v24
	v_add_f32_e32 v17, v197, v17
	v_add_f32_e32 v25, v205, v25
	v_add_f32_e32 v18, v198, v18
	v_add_f32_e32 v26, v206, v26
	v_add_f32_e32 v19, v199, v19
	v_add_f32_e32 v27, v207, v27
	v_add_f32_e32 v20, v200, v20
	v_add_f32_e32 v28, v208, v28
	v_add_f32_e32 v21, v201, v21
	v_add_f32_e32 v29, v209, v29
	v_add_f32_e32 v22, v202, v22
	v_add_f32_e32 v30, v210, v30
	v_add_f32_e32 v23, v203, v23
	v_add_f32_e32 v31, v211, v31
	v_mul_f32_e32 v32, 0xbfb8aa3b, v16
	v_mul_f32_e32 v33, 0xbfb8aa3b, v17
	v_mul_f32_e32 v34, 0xbfb8aa3b, v18
	v_mul_f32_e32 v35, 0xbfb8aa3b, v19
	v_mul_f32_e32 v36, 0xbfb8aa3b, v20
	v_mul_f32_e32 v37, 0xbfb8aa3b, v21
	v_mul_f32_e32 v38, 0xbfb8aa3b, v22
	v_mul_f32_e32 v39, 0xbfb8aa3b, v23
	v_exp_f32_e32 v32, v32
	v_exp_f32_e32 v33, v33
	v_exp_f32_e32 v34, v34
	v_exp_f32_e32 v35, v35
	v_exp_f32_e32 v36, v36
	v_exp_f32_e32 v37, v37
	v_exp_f32_e32 v38, v38
	v_exp_f32_e32 v39, v39
	s_nop 0
	v_add_f32_e32 v32, 1.0, v32
	v_add_f32_e32 v33, 1.0, v33
	v_add_f32_e32 v34, 1.0, v34
	v_add_f32_e32 v35, 1.0, v35
	v_add_f32_e32 v36, 1.0, v36
	v_add_f32_e32 v37, 1.0, v37
	v_add_f32_e32 v38, 1.0, v38
	v_add_f32_e32 v39, 1.0, v39
	v_rcp_f32_e32 v32, v32
	v_rcp_f32_e32 v33, v33
	v_rcp_f32_e32 v34, v34
	v_rcp_f32_e32 v35, v35
	v_rcp_f32_e32 v36, v36
	v_rcp_f32_e32 v37, v37
	v_rcp_f32_e32 v38, v38
	v_rcp_f32_e32 v39, v39
	s_nop 0
	v_mul_f32_e32 v16, v16, v32
	v_mul_f32_e32 v17, v17, v33
	v_mul_f32_e32 v18, v18, v34
	v_mul_f32_e32 v19, v19, v35
	v_mul_f32_e32 v20, v20, v36
	v_mul_f32_e32 v21, v21, v37
	v_mul_f32_e32 v22, v22, v38
	v_mul_f32_e32 v23, v23, v39
	v_mul_f32_e32 v16, v16, v24
	v_mul_f32_e32 v17, v17, v25
	v_mul_f32_e32 v18, v18, v26
	v_mul_f32_e32 v19, v19, v27
	v_mul_f32_e32 v20, v20, v28
	v_mul_f32_e32 v21, v21, v29
	v_mul_f32_e32 v22, v22, v30
	v_mul_f32_e32 v23, v23, v31
	v_cvt_pk_bf16_f32 v40, v16, v17
	v_cvt_pk_bf16_f32 v41, v18, v19
	v_cvt_pk_bf16_f32 v42, v20, v21
	v_cvt_pk_bf16_f32 v43, v22, v23
	s_nop 0
	global_store_dwordx4 v14, v[40:43], s[48:49]
	s_add_u32 s4, s4, s5
	s_cmp_lt_u32 s4, 0x122
	s_cbranch_scc1 .Lffx_loop
